# v120 plus one static s_setprio 1 for waves 0-3 before every GEMM K loop
# speedup vs baseline: 1.0044x; 1.0005x over previous
; #define GPTR(T, ptr) ((__attribute__((address_space(1))) T*)(ptr))
; __device__ __forceinline__ float frsq(float x) { return __builtin_amdgcn_rsqf(x); }
; __device__ __forceinline__ int ptid_(int wave) { int l_; asm volatile("v_mbcnt_lo_u32_b32 %0, -1, 0\n\tv_mbcnt_hi_u32_b32 %0, -1, %0" : "=v"(l_)); return (wave << 6) | l_; }
; #define STAGE_B(P, br, kt) do { const char* _gb = (const char*)(Bt + ((long)(br) * K + (long)(kt) * BK)); \
;     __builtin_amdgcn_global_load_lds((const unsigned*)(_gb + bofl0), (unsigned*)((char*)(P) + gtid_ * 16), 16, 0, 0); \
;     __builtin_amdgcn_global_load_lds((const unsigned*)(_gb + (long)K * 128 + bofl0), (unsigned*)((char*)(P) + gtid_ * 16 + 8192), 16, 0, 0); } while (0)
; #define BAR __builtin_amdgcn_s_barrier()
; template <int EPI>
; __device__ __forceinline__ void gemm_tile(const GemmArgs& g, int brow, int bcol, int parity, bool first, bool nvalid, int nbrow, int nbcol) {
;     ...
;   int gtid_ = ptid_(g.tid);
;   const int wid = gtid_ >> 6, lane = gtid_ & 63, wr = wid >> 2, wc = wid & 3, fr = lane & 15, fq = lane >> 4;
;   unsigned aofl0, bofl0;
;   { int _r, _c; stage_rc(gtid_ * 16, _r, _c); aofl0 = (unsigned)(_r * lda + _c) * 2u; bofl0 = (unsigned)(_r * K + _c) * 2u; }
;   f32x4 acc[2][2][4][2] = {};
;   bf16x8 At[4][2], B0[2][2], B1[2][2];
;   const int nt = K / BK;
;   float* rstd_s = (float*)(smem + 153600) + (parity & 1) * 256;
;   if (first) {
;     WAIT_V(0);
;     __syncthreads();
;     STAGE_B(SB(0, 0), bcol, 0); STAGE_A(SA(0, 0), brow, 0);
;     STAGE_B(SB(0, 1), bcol + HALF, 0); STAGE_A(SA(0, 1), brow + HALF, 0);
;   }
;   f32x4 ra0, ra1, ra2, ra3;
;   if constexpr (EPI != EPI_RES) {
;     if (gtid_ < 256) {
;       const __attribute__((address_space(1))) f32x4* pp = GPTR(const f32x4, g.rowss + (long)(brow + gtid_) * 16);
;       ra0 = pp[0]; ra1 = pp[1]; ra2 = pp[2]; ra3 = pp[3];
;     }
;   }
;   if (wr == 1) BAR;
;   if (first) { WAIT_V(4); } else { WAIT_V(0); }
;   BAR;
;   if constexpr (EPI != EPI_RES) {
;     if (gtid_ < 256) {
;       float s = ((ra0[0] + ra0[1]) + (ra0[2] + ra0[3])) + ((ra1[0] + ra1[1]) + (ra1[2] + ra1[3])) + ((ra2[0] + ra2[1]) + (ra2[2] + ra2[3])) + ((ra3[0] + ra3[1]) + (ra3[2] + ra3[3]));
;       rstd_s[gtid_] = frsq(s * (1.0f / 1024.0f) + 1e-6f);
;     }
;   }
;   STAGE_B(SB(1, 0), bcol, 1); STAGE_A(SA(1, 0), brow, 1); STAGE_B(SB(1, 1), bcol + HALF, 1);
;   WAIT_V(6); BAR;
.LBB0_89:
	s_or_b64 exec, exec, s[14:15]
	s_ashr_i32 s13, s12, 31
	s_lshl_b64 s[26:27], s[12:13], 11
	s_add_u32 s0, s22, s26
	v_readlane_b32 s13, v254, 8
	s_addc_u32 s1, s23, s27
	s_waitcnt vmcnt(0)
	v_lshl_add_u64 v[2:3], s[0:1], 0, v[0:1]
	v_add_u32_e32 v150, s13, v142
	s_mov_b64 s[14:15], 0x80
	v_readfirstlane_b32 s0, v150
	v_add_u32_e32 v151, 0x2000, v150
	v_lshl_add_u64 v[4:5], v[2:3], 0, s[14:15]
	s_mov_b32 m0, s0
	v_readfirstlane_b32 s0, v151
	s_ashr_i32 s39, s38, 31
	global_load_lds_dwordx4 v[4:5], off
	s_mov_b32 m0, s0
	s_lshl_b64 s[0:1], s[38:39], 11
	s_mov_b64 s[36:37], 0x20080
	s_add_u32 s0, s80, s0
	v_lshl_add_u64 v[2:3], v[2:3], 0, s[36:37]
	s_addc_u32 s1, s81, s1
	v_add_u32_e32 v152, 0x8000, v137
	global_load_lds_dwordx4 v[2:3], off
	v_lshl_add_u64 v[2:3], s[0:1], 0, v[0:1]
	v_readfirstlane_b32 s0, v152
	v_add_u32_e32 v153, 0xa000, v137
	v_lshl_add_u64 v[4:5], v[2:3], 0, s[14:15]
	s_mov_b32 m0, s0
	v_readfirstlane_b32 s0, v153
	global_load_lds_dwordx4 v[4:5], off
	s_mov_b32 m0, s0
	s_or_b32 s0, s12, 0x80
	s_ashr_i32 s1, s0, 31
	s_lshl_b64 s[0:1], s[0:1], 11
	s_add_u32 s0, s22, s0
	v_lshl_add_u64 v[2:3], v[2:3], 0, s[36:37]
	s_addc_u32 s1, s23, s1
	global_load_lds_dwordx4 v[2:3], off
	v_lshl_add_u64 v[2:3], s[0:1], 0, v[0:1]
	v_readlane_b32 s1, v254, 9
	v_lshl_add_u64 v[4:5], v[2:3], 0, s[14:15]
	v_lshl_add_u64 v[2:3], v[2:3], 0, s[36:37]
	v_add_u32_e32 v155, s1, v142
	v_add_u32_e32 v156, 0x2000, v155
	v_readfirstlane_b32 s0, v155
	s_mov_b32 m0, s0
	v_readfirstlane_b32 s0, v156
	global_load_lds_dwordx4 v[4:5], off
	s_mov_b32 m0, s0
	v_and_b32_e32 v139, 15, v132
	global_load_lds_dwordx4 v[2:3], off
	v_lshlrev_b32_e32 v5, 2, v132
	v_and_b32_e32 v2, 48, v132
	v_lshlrev_b32_e32 v4, 6, v139
	v_and_b32_e32 v5, 32, v5
	v_bitop3_b32 v4, v4, v5, v2 bitop3:0x36
	v_readlane_b32 s0, v254, 7
	v_lshlrev_b32_e32 v11, 6, v132
	v_add_u32_e32 v9, s1, v4
	v_add_u32_e32 v7, s0, v4
	s_movk_i32 s0, 0x3c0
	v_and_or_b32 v2, v11, s0, v2
	s_add_i32 s0, s2, s3
	v_xad_u32 v5, v2, v5, 0
	v_lshlrev_b32_e32 v2, 14, v18
	s_ashr_i32 s1, s0, 31
	s_add_i32 s14, 0, 0x10000
	v_and_b32_e32 v2, 0xffff8000, v2
	s_lshl_b64 s[0:1], s[0:1], 11
	v_ashrrev_i32_e32 v140, 6, v138
	v_lshl_add_u32 v2, v19, 11, v2
	v_and_b32_e32 v14, 1, v18
	s_add_u32 s0, s10, s0
	v_and_b32_e32 v141, 3, v140
	s_waitcnt vmcnt(6)
	v_lshlrev_b32_e32 v10, 13, v21
	v_lshl_or_b32 v2, v14, 6, v2
	s_addc_u32 s1, s11, s1
	v_lshlrev_b32_e32 v3, 12, v141
	v_add_u32_e32 v6, s14, v4
	v_add_u32_e32 v8, s13, v4
	v_add_u32_e32 v4, 0, v4
	v_or_b32_e32 v11, 0x800, v10
	v_or_b32_e32 v12, 0x1000, v10
	v_or_b32_e32 v13, 0x1800, v10
	v_lshl_add_u32 v130, v20, 1, v2
	s_add_u32 s12, s73, s26
	v_readlane_b32 s2, v255, 0
	v_mov_b32_e32 v2, 0
	v_lshlrev_b32_e32 v143, 6, v21
	v_mov_b32_e32 v131, v1
	s_addc_u32 s13, s2, s27
	s_mov_b32 s15, -2
	v_add_u32_e32 v157, v6, v3
	v_add_u32_e32 v147, v4, v10
	v_add_u32_e32 v146, v5, v11
	v_add_u32_e32 v145, v5, v12
	v_add_u32_e32 v144, v5, v13
	v_add_u32_e32 v154, v7, v3
	v_add_u32_e32 v149, v8, v3
	v_add_u32_e32 v148, v9, v3
	v_mov_b32_e32 v3, v2
	v_mov_b32_e32 v4, v2
	v_mov_b32_e32 v5, v2
	v_mov_b32_e32 v6, v2
	v_mov_b32_e32 v7, v2
	v_mov_b32_e32 v8, v2
	v_mov_b32_e32 v9, v2
	v_mov_b32_e32 v10, v2
	v_mov_b32_e32 v11, v2
	v_mov_b32_e32 v12, v2
	v_mov_b32_e32 v13, v2
	v_mov_b32_e32 v14, v2
	v_mov_b32_e32 v15, v2
	v_mov_b32_e32 v16, v2
	v_mov_b32_e32 v17, v2
	v_mov_b32_e32 v18, v2
	v_mov_b32_e32 v19, v2
	v_mov_b32_e32 v20, v2
	v_mov_b32_e32 v21, v2
	v_mov_b32_e32 v22, v2
	v_mov_b32_e32 v23, v2
	v_mov_b32_e32 v24, v2
	v_mov_b32_e32 v25, v2
	v_mov_b32_e32 v26, v2
	v_mov_b32_e32 v27, v2
	v_mov_b32_e32 v28, v2
	v_mov_b32_e32 v29, v2
	v_mov_b32_e32 v30, v2
	v_mov_b32_e32 v31, v2
	v_mov_b32_e32 v32, v2
	v_mov_b32_e32 v33, v2
	v_mov_b32_e32 v34, v2
	v_mov_b32_e32 v35, v2
	v_mov_b32_e32 v36, v2
	v_mov_b32_e32 v37, v2
	v_mov_b32_e32 v38, v2
	v_mov_b32_e32 v39, v2
	v_mov_b32_e32 v40, v2
	v_mov_b32_e32 v41, v2
	v_mov_b32_e32 v42, v2
	v_mov_b32_e32 v43, v2
	v_mov_b32_e32 v44, v2
	v_mov_b32_e32 v45, v2
	v_mov_b32_e32 v46, v2
	v_mov_b32_e32 v47, v2
	v_mov_b32_e32 v48, v2
	v_mov_b32_e32 v49, v2
	v_mov_b32_e32 v50, v2
	v_mov_b32_e32 v51, v2
	v_mov_b32_e32 v52, v2
	v_mov_b32_e32 v53, v2
	v_mov_b32_e32 v54, v2
	v_mov_b32_e32 v55, v2
	v_mov_b32_e32 v56, v2
	v_mov_b32_e32 v57, v2
	v_mov_b32_e32 v58, v2
	v_mov_b32_e32 v59, v2
	v_mov_b32_e32 v60, v2
	v_mov_b32_e32 v61, v2
	v_mov_b32_e32 v62, v2
	v_mov_b32_e32 v63, v2
	v_mov_b32_e32 v64, v2
	v_mov_b32_e32 v65, v2
	v_mov_b32_e32 v66, v2
	v_mov_b32_e32 v67, v2
	v_mov_b32_e32 v68, v2
	v_mov_b32_e32 v69, v2
	v_mov_b32_e32 v70, v2
	v_mov_b32_e32 v71, v2
	v_mov_b32_e32 v72, v2
	v_mov_b32_e32 v73, v2
	v_mov_b32_e32 v74, v2
	v_mov_b32_e32 v75, v2
	v_mov_b32_e32 v76, v2
	v_mov_b32_e32 v77, v2
	v_mov_b32_e32 v78, v2
	v_mov_b32_e32 v79, v2
	v_mov_b32_e32 v80, v2
	v_mov_b32_e32 v81, v2
	v_mov_b32_e32 v82, v2
	v_mov_b32_e32 v83, v2
	v_mov_b32_e32 v84, v2
	v_mov_b32_e32 v85, v2
	v_mov_b32_e32 v86, v2
	v_mov_b32_e32 v87, v2
	v_mov_b32_e32 v88, v2
	v_mov_b32_e32 v89, v2
	v_mov_b32_e32 v90, v2
	v_mov_b32_e32 v91, v2
	v_mov_b32_e32 v92, v2
	v_mov_b32_e32 v93, v2
	v_mov_b32_e32 v94, v2
	v_mov_b32_e32 v95, v2
	v_mov_b32_e32 v96, v2
	v_mov_b32_e32 v97, v2
	v_mov_b32_e32 v98, v2
	v_mov_b32_e32 v99, v2
	v_mov_b32_e32 v100, v2
	v_mov_b32_e32 v101, v2
	v_mov_b32_e32 v102, v2
	v_mov_b32_e32 v103, v2
	v_mov_b32_e32 v104, v2
	v_mov_b32_e32 v105, v2
	v_mov_b32_e32 v106, v2
	v_mov_b32_e32 v107, v2
	v_mov_b32_e32 v108, v2
	v_mov_b32_e32 v109, v2
	v_mov_b32_e32 v110, v2
	v_mov_b32_e32 v111, v2
	v_mov_b32_e32 v112, v2
	v_mov_b32_e32 v113, v2
	v_mov_b32_e32 v114, v2
	v_mov_b32_e32 v115, v2
	v_mov_b32_e32 v116, v2
	v_mov_b32_e32 v117, v2
	v_mov_b32_e32 v118, v2
	v_mov_b32_e32 v119, v2
	v_mov_b32_e32 v120, v2
	v_mov_b32_e32 v121, v2
	v_mov_b32_e32 v122, v2
	v_mov_b32_e32 v123, v2
	v_mov_b32_e32 v124, v2
	v_mov_b32_e32 v125, v2
	v_mov_b32_e32 v126, v2
	v_mov_b32_e32 v127, v2
	v_mov_b32_e32 v128, v2
	v_mov_b32_e32 v129, v2
	s_mov_b64 s[26:27], 0x8240080
	s_mov_b64 s[36:37], 0x8260080
	s_mov_b64 s[40:41], 0x8200100
	s_mov_b64 s[44:45], 0x8220100
	s_mov_b64 s[46:47], 0x8240100
	s_mov_b64 s[48:49], 0x8260100
	s_mov_b64 s[50:51], 0x8200180
	s_mov_b64 s[52:53], 0x8220180
	s_cmp_ge_u32 s33, 0x100
	s_cbranch_scc1 .Lprio_done_0
	s_setprio 1

; #define GPTR(T, ptr) ((__attribute__((address_space(1))) T*)(ptr))
; __device__ __forceinline__ float frsq(float x) { return __builtin_amdgcn_rsqf(x); }
; __device__ __forceinline__ int ptid_(int wave) { int l_; asm volatile("v_mbcnt_lo_u32_b32 %0, -1, 0\n\tv_mbcnt_hi_u32_b32 %0, -1, %0" : "=v"(l_)); return (wave << 6) | l_; }
; #define STAGE_B(P, br, kt) do { const char* _gb = (const char*)(Bt + ((long)(br) * K + (long)(kt) * BK)); \
;     __builtin_amdgcn_global_load_lds((const unsigned*)(_gb + bofl0), (unsigned*)((char*)(P) + gtid_ * 16), 16, 0, 0); \
;     __builtin_amdgcn_global_load_lds((const unsigned*)(_gb + (long)K * 128 + bofl0), (unsigned*)((char*)(P) + gtid_ * 16 + 8192), 16, 0, 0); } while (0)
; #define BAR __builtin_amdgcn_s_barrier()
; template <int EPI>
; __device__ __forceinline__ void gemm_tile(const GemmArgs& g, int brow, int bcol, int parity, bool first, bool nvalid, int nbrow, int nbcol) {
;     ...
;   int gtid_ = ptid_(g.tid);
;   const int wid = gtid_ >> 6, lane = gtid_ & 63, wr = wid >> 2, wc = wid & 3, fr = lane & 15, fq = lane >> 4;
;   unsigned aofl0, bofl0;
;   { int _r, _c; stage_rc(gtid_ * 16, _r, _c); aofl0 = (unsigned)(_r * lda + _c) * 2u; bofl0 = (unsigned)(_r * K + _c) * 2u; }
;   f32x4 acc[2][2][4][2] = {};
;   bf16x8 At[4][2], B0[2][2], B1[2][2];
;   const int nt = K / BK;
;   float* rstd_s = (float*)(smem + 153600) + (parity & 1) * 256;
;   if (first) {
;     WAIT_V(0);
;     __syncthreads();
;     STAGE_B(SB(0, 0), bcol, 0); STAGE_A(SA(0, 0), brow, 0);
;     STAGE_B(SB(0, 1), bcol + HALF, 0); STAGE_A(SA(0, 1), brow + HALF, 0);
;   }
;   f32x4 ra0, ra1, ra2, ra3;
;   if constexpr (EPI != EPI_RES) {
;     if (gtid_ < 256) {
;       const __attribute__((address_space(1))) f32x4* pp = GPTR(const f32x4, g.rowss + (long)(brow + gtid_) * 16);
;       ra0 = pp[0]; ra1 = pp[1]; ra2 = pp[2]; ra3 = pp[3];
;     }
;   }
;   if (wr == 1) BAR;
;   if (first) { WAIT_V(4); } else { WAIT_V(0); }
;   BAR;
;   if constexpr (EPI != EPI_RES) {
;     if (gtid_ < 256) {
;       float s = ((ra0[0] + ra0[1]) + (ra0[2] + ra0[3])) + ((ra1[0] + ra1[1]) + (ra1[2] + ra1[3])) + ((ra2[0] + ra2[1]) + (ra2[2] + ra2[3])) + ((ra3[0] + ra3[1]) + (ra3[2] + ra3[3]));
;       rstd_s[gtid_] = frsq(s * (1.0f / 1024.0f) + 1e-6f);
;     }
;   }
;   STAGE_B(SB(1, 0), bcol, 1); STAGE_A(SA(1, 0), brow, 1); STAGE_B(SB(1, 1), bcol + HALF, 1);
;   WAIT_V(6); BAR;
.LBB0_132:
	s_or_b64 exec, exec, s[12:13]
	s_ashr_i32 s39, s38, 31
	s_lshl_b64 s[0:1], s[38:39], 11
	s_add_u32 s0, s73, s0
	v_readlane_b32 s15, v255, 0
	v_readlane_b32 s22, v254, 8
	s_addc_u32 s1, s15, s1
	s_waitcnt vmcnt(0)
	v_lshl_add_u64 v[2:3], s[0:1], 0, v[0:1]
	v_add_u32_e32 v149, s22, v141
	s_mov_b64 s[24:25], 0x80
	v_readfirstlane_b32 s12, v149
	v_add_u32_e32 v151, 0x2000, v149
	v_lshl_add_u64 v[4:5], v[2:3], 0, s[24:25]
	s_mov_b32 m0, s12
	v_readfirstlane_b32 s12, v151
	s_ashr_i32 s41, s40, 31
	global_load_lds_dwordx4 v[4:5], off
	s_mov_b32 m0, s12
	s_lshl_b64 s[12:13], s[40:41], 11
	s_mov_b64 s[34:35], 0x20080
	s_add_u32 s12, s80, s12
	v_lshl_add_u64 v[2:3], v[2:3], 0, s[34:35]
	s_addc_u32 s13, s81, s13
	v_add_u32_e32 v152, 0x8000, v137
	global_load_lds_dwordx4 v[2:3], off
	v_lshl_add_u64 v[2:3], s[12:13], 0, v[0:1]
	v_readfirstlane_b32 s12, v152
	v_add_u32_e32 v153, 0xa000, v137
	v_lshl_add_u64 v[4:5], v[2:3], 0, s[24:25]
	s_mov_b32 m0, s12
	v_readfirstlane_b32 s12, v153
	global_load_lds_dwordx4 v[4:5], off
	s_mov_b32 m0, s12
	s_or_b32 s12, s38, 0x80
	s_ashr_i32 s13, s12, 31
	s_lshl_b64 s[12:13], s[12:13], 11
	s_add_u32 s12, s73, s12
	v_lshl_add_u64 v[2:3], v[2:3], 0, s[34:35]
	s_addc_u32 s13, s15, s13
	global_load_lds_dwordx4 v[2:3], off
	v_lshl_add_u64 v[2:3], s[12:13], 0, v[0:1]
	v_readlane_b32 s13, v254, 9
	v_lshl_add_u64 v[4:5], v[2:3], 0, s[24:25]
	v_lshl_add_u64 v[2:3], v[2:3], 0, s[34:35]
	v_add_u32_e32 v155, s13, v141
	v_add_u32_e32 v156, 0x2000, v155
	v_readfirstlane_b32 s12, v155
	s_mov_b32 m0, s12
	v_readfirstlane_b32 s12, v156
	global_load_lds_dwordx4 v[4:5], off
	s_mov_b32 m0, s12
	v_and_b32_e32 v150, 15, v132
	global_load_lds_dwordx4 v[2:3], off
	v_lshlrev_b32_e32 v5, 2, v132
	v_and_b32_e32 v2, 48, v132
	v_lshlrev_b32_e32 v4, 6, v150
	v_and_b32_e32 v5, 32, v5
	v_bitop3_b32 v4, v4, v5, v2 bitop3:0x36
	v_readlane_b32 s12, v254, 7
	v_lshlrev_b32_e32 v11, 6, v132
	s_add_i32 s2, s2, s3
	v_add_u32_e32 v7, s12, v4
	s_movk_i32 s12, 0x3c0
	v_and_or_b32 v2, v11, s12, v2
	v_xad_u32 v5, v2, v5, 0
	v_lshlrev_b32_e32 v2, 14, v18
	v_and_b32_e32 v2, 0xffff8000, v2
	v_ashrrev_i32_e32 v139, 6, v138
	v_lshl_add_u32 v2, v19, 11, v2
	v_and_b32_e32 v14, 1, v18
	s_ashr_i32 s3, s2, 31
	v_and_b32_e32 v140, 3, v139
	s_waitcnt vmcnt(6)
	s_add_i32 s15, 0, 0x10000
	v_lshlrev_b32_e32 v10, 13, v21
	v_lshl_or_b32 v2, v14, 6, v2
	s_lshl_b64 s[2:3], s[2:3], 11
	v_lshlrev_b32_e32 v3, 12, v140
	v_add_u32_e32 v6, s15, v4
	v_add_u32_e32 v8, s22, v4
	v_add_u32_e32 v9, s13, v4
	v_add_u32_e32 v4, 0, v4
	v_or_b32_e32 v11, 0x800, v10
	v_or_b32_e32 v12, 0x1000, v10
	v_or_b32_e32 v13, 0x1800, v10
	v_lshl_add_u32 v130, v20, 1, v2
	s_add_u32 s12, s10, s2
	v_mov_b32_e32 v2, 0
	s_mov_b64 s[26:27], 0x80
	v_lshlrev_b32_e32 v142, 6, v21
	v_mov_b32_e32 v131, v1
	s_addc_u32 s13, s11, s3
	s_mov_b32 s22, -2
	v_add_u32_e32 v157, v6, v3
	v_add_u32_e32 v146, v4, v10
	v_add_u32_e32 v145, v5, v11
	v_add_u32_e32 v144, v5, v12
	v_add_u32_e32 v143, v5, v13
	v_add_u32_e32 v154, v7, v3
	v_add_u32_e32 v148, v8, v3
	v_add_u32_e32 v147, v9, v3
	v_mov_b32_e32 v3, v2
	v_mov_b32_e32 v4, v2
	v_mov_b32_e32 v5, v2
	v_mov_b32_e32 v6, v2
	v_mov_b32_e32 v7, v2
	v_mov_b32_e32 v8, v2
	v_mov_b32_e32 v9, v2
	v_mov_b32_e32 v10, v2
	v_mov_b32_e32 v11, v2
	v_mov_b32_e32 v12, v2
	v_mov_b32_e32 v13, v2
	v_mov_b32_e32 v14, v2
	v_mov_b32_e32 v15, v2
	v_mov_b32_e32 v16, v2
	v_mov_b32_e32 v17, v2
	v_mov_b32_e32 v18, v2
	v_mov_b32_e32 v19, v2
	v_mov_b32_e32 v20, v2
	v_mov_b32_e32 v21, v2
	v_mov_b32_e32 v22, v2
	v_mov_b32_e32 v23, v2
	v_mov_b32_e32 v24, v2
	v_mov_b32_e32 v25, v2
	v_mov_b32_e32 v26, v2
	v_mov_b32_e32 v27, v2
	v_mov_b32_e32 v28, v2
	v_mov_b32_e32 v29, v2
	v_mov_b32_e32 v30, v2
	v_mov_b32_e32 v31, v2
	v_mov_b32_e32 v32, v2
	v_mov_b32_e32 v33, v2
	v_mov_b32_e32 v34, v2
	v_mov_b32_e32 v35, v2
	v_mov_b32_e32 v36, v2
	v_mov_b32_e32 v37, v2
	v_mov_b32_e32 v38, v2
	v_mov_b32_e32 v39, v2
	v_mov_b32_e32 v40, v2
	v_mov_b32_e32 v41, v2
	v_mov_b32_e32 v42, v2
	v_mov_b32_e32 v43, v2
	v_mov_b32_e32 v44, v2
	v_mov_b32_e32 v45, v2
	v_mov_b32_e32 v46, v2
	v_mov_b32_e32 v47, v2
	v_mov_b32_e32 v48, v2
	v_mov_b32_e32 v49, v2
	v_mov_b32_e32 v50, v2
	v_mov_b32_e32 v51, v2
	v_mov_b32_e32 v52, v2
	v_mov_b32_e32 v53, v2
	v_mov_b32_e32 v54, v2
	v_mov_b32_e32 v55, v2
	v_mov_b32_e32 v56, v2
	v_mov_b32_e32 v57, v2
	v_mov_b32_e32 v58, v2
	v_mov_b32_e32 v59, v2
	v_mov_b32_e32 v60, v2
	v_mov_b32_e32 v61, v2
	v_mov_b32_e32 v62, v2
	v_mov_b32_e32 v63, v2
	v_mov_b32_e32 v64, v2
	v_mov_b32_e32 v65, v2
	v_mov_b32_e32 v66, v2
	v_mov_b32_e32 v67, v2
	v_mov_b32_e32 v68, v2
	v_mov_b32_e32 v69, v2
	v_mov_b32_e32 v70, v2
	v_mov_b32_e32 v71, v2
	v_mov_b32_e32 v72, v2
	v_mov_b32_e32 v73, v2
	v_mov_b32_e32 v74, v2
	v_mov_b32_e32 v75, v2
	v_mov_b32_e32 v76, v2
	v_mov_b32_e32 v77, v2
	v_mov_b32_e32 v78, v2
	v_mov_b32_e32 v79, v2
	v_mov_b32_e32 v80, v2
	v_mov_b32_e32 v81, v2
	v_mov_b32_e32 v82, v2
	v_mov_b32_e32 v83, v2
	v_mov_b32_e32 v84, v2
	v_mov_b32_e32 v85, v2
	v_mov_b32_e32 v86, v2
	v_mov_b32_e32 v87, v2
	v_mov_b32_e32 v88, v2
	v_mov_b32_e32 v89, v2
	v_mov_b32_e32 v90, v2
	v_mov_b32_e32 v91, v2
	v_mov_b32_e32 v92, v2
	v_mov_b32_e32 v93, v2
	v_mov_b32_e32 v94, v2
	v_mov_b32_e32 v95, v2
	v_mov_b32_e32 v96, v2
	v_mov_b32_e32 v97, v2
	v_mov_b32_e32 v98, v2
	v_mov_b32_e32 v99, v2
	v_mov_b32_e32 v100, v2
	v_mov_b32_e32 v101, v2
	v_mov_b32_e32 v102, v2
	v_mov_b32_e32 v103, v2
	v_mov_b32_e32 v104, v2
	v_mov_b32_e32 v105, v2
	v_mov_b32_e32 v106, v2
	v_mov_b32_e32 v107, v2
	v_mov_b32_e32 v108, v2
	v_mov_b32_e32 v109, v2
	v_mov_b32_e32 v110, v2
	v_mov_b32_e32 v111, v2
	v_mov_b32_e32 v112, v2
	v_mov_b32_e32 v113, v2
	v_mov_b32_e32 v114, v2
	v_mov_b32_e32 v115, v2
	v_mov_b32_e32 v116, v2
	v_mov_b32_e32 v117, v2
	v_mov_b32_e32 v118, v2
	v_mov_b32_e32 v119, v2
	v_mov_b32_e32 v120, v2
	v_mov_b32_e32 v121, v2
	v_mov_b32_e32 v122, v2
	v_mov_b32_e32 v123, v2
	v_mov_b32_e32 v124, v2
	v_mov_b32_e32 v125, v2
	v_mov_b32_e32 v126, v2
	v_mov_b32_e32 v127, v2
	v_mov_b32_e32 v128, v2
	v_mov_b32_e32 v129, v2
	s_mov_b64 s[24:25], 0x8240080
	s_mov_b64 s[34:35], 0x8260080
	s_mov_b64 s[36:37], 0x8200100
	s_mov_b64 s[42:43], 0x8220100
	s_mov_b64 s[44:45], 0x8240100
	s_mov_b64 s[46:47], 0x8260100
	s_mov_b64 s[48:49], 0x8200180
	s_mov_b64 s[50:51], 0x8220180
	s_mov_b64 s[52:53], 0x20100
	s_mov_b64 s[56:57], 0x40100
	s_mov_b64 s[66:67], 0x60100
	s_mov_b64 s[76:77], 0x20180
	s_mov_b64 s[96:97], 0x40180
	s_mov_b64 s[60:61], 0x60180
	s_cmp_ge_u32 s33, 0x100
	s_cbranch_scc1 .Lprio_done_1
	s_setprio 1

; #define GPTR(T, ptr) ((__attribute__((address_space(1))) T*)(ptr))
; __device__ __forceinline__ float frsq(float x) { return __builtin_amdgcn_rsqf(x); }
; __device__ __forceinline__ int ptid_(int wave) { int l_; asm volatile("v_mbcnt_lo_u32_b32 %0, -1, 0\n\tv_mbcnt_hi_u32_b32 %0, -1, %0" : "=v"(l_)); return (wave << 6) | l_; }
; #define STAGE_B(P, br, kt) do { const char* _gb = (const char*)(Bt + ((long)(br) * K + (long)(kt) * BK)); \
;     __builtin_amdgcn_global_load_lds((const unsigned*)(_gb + bofl0), (unsigned*)((char*)(P) + gtid_ * 16), 16, 0, 0); \
;     __builtin_amdgcn_global_load_lds((const unsigned*)(_gb + (long)K * 128 + bofl0), (unsigned*)((char*)(P) + gtid_ * 16 + 8192), 16, 0, 0); } while (0)
; #define BAR __builtin_amdgcn_s_barrier()
; template <int EPI>
; __device__ __forceinline__ void gemm_tile(const GemmArgs& g, int brow, int bcol, int parity, bool first, bool nvalid, int nbrow, int nbcol) {
;     ...
;   int gtid_ = ptid_(g.tid);
;   const int wid = gtid_ >> 6, lane = gtid_ & 63, wr = wid >> 2, wc = wid & 3, fr = lane & 15, fq = lane >> 4;
;   unsigned aofl0, bofl0;
;   { int _r, _c; stage_rc(gtid_ * 16, _r, _c); aofl0 = (unsigned)(_r * lda + _c) * 2u; bofl0 = (unsigned)(_r * K + _c) * 2u; }
;   f32x4 acc[2][2][4][2] = {};
;   bf16x8 At[4][2], B0[2][2], B1[2][2];
;   const int nt = K / BK;
;   float* rstd_s = (float*)(smem + 153600) + (parity & 1) * 256;
;   if (first) {
;     WAIT_V(0);
;     __syncthreads();
;     STAGE_B(SB(0, 0), bcol, 0); STAGE_A(SA(0, 0), brow, 0);
;     STAGE_B(SB(0, 1), bcol + HALF, 0); STAGE_A(SA(0, 1), brow + HALF, 0);
;   }
;   f32x4 ra0, ra1, ra2, ra3;
;   if constexpr (EPI != EPI_RES) {
;     if (gtid_ < 256) {
;       const __attribute__((address_space(1))) f32x4* pp = GPTR(const f32x4, g.rowss + (long)(brow + gtid_) * 16);
;       ra0 = pp[0]; ra1 = pp[1]; ra2 = pp[2]; ra3 = pp[3];
;     }
;   }
;   if (wr == 1) BAR;
;   if (first) { WAIT_V(4); } else { WAIT_V(0); }
;   BAR;
;   if constexpr (EPI != EPI_RES) {
;     if (gtid_ < 256) {
;       float s = ((ra0[0] + ra0[1]) + (ra0[2] + ra0[3])) + ((ra1[0] + ra1[1]) + (ra1[2] + ra1[3])) + ((ra2[0] + ra2[1]) + (ra2[2] + ra2[3])) + ((ra3[0] + ra3[1]) + (ra3[2] + ra3[3]));
;       rstd_s[gtid_] = frsq(s * (1.0f / 1024.0f) + 1e-6f);
;     }
;   }
;   STAGE_B(SB(1, 0), bcol, 1); STAGE_A(SA(1, 0), brow, 1); STAGE_B(SB(1, 1), bcol + HALF, 1);
;   WAIT_V(6); BAR;
.LBB0_165:
	s_or_b64 exec, exec, s[12:13]
	s_ashr_i32 s41, s40, 31
	s_lshl_b64 s[12:13], s[40:41], 11
	s_add_u32 s0, s19, s12
	v_readlane_b32 s25, v254, 8
	s_addc_u32 s1, s21, s13
	s_waitcnt vmcnt(0)
	v_lshl_add_u64 v[2:3], s[0:1], 0, v[0:1]
	v_add_u32_e32 v150, s25, v142
	s_mov_b64 s[26:27], 0x80
	v_readfirstlane_b32 s0, v150
	v_add_u32_e32 v151, 0x2000, v150
	v_lshl_add_u64 v[4:5], v[2:3], 0, s[26:27]
	s_mov_b32 m0, s0
	v_readfirstlane_b32 s0, v151
	s_ashr_i32 s39, s38, 31
	global_load_lds_dwordx4 v[4:5], off
	s_mov_b32 m0, s0
	s_lshl_b64 s[0:1], s[38:39], 11
	s_mov_b64 s[42:43], 0x20080
	s_add_u32 s0, s80, s0
	v_lshl_add_u64 v[2:3], v[2:3], 0, s[42:43]
	s_addc_u32 s1, s81, s1
	v_add_u32_e32 v152, 0x8000, v137
	global_load_lds_dwordx4 v[2:3], off
	v_lshl_add_u64 v[2:3], s[0:1], 0, v[0:1]
	v_readfirstlane_b32 s0, v152
	v_add_u32_e32 v153, 0xa000, v137
	v_lshl_add_u64 v[4:5], v[2:3], 0, s[26:27]
	s_mov_b32 m0, s0
	v_readfirstlane_b32 s0, v153
	global_load_lds_dwordx4 v[4:5], off
	s_mov_b32 m0, s0
	s_or_b32 s0, s40, 0x80
	s_ashr_i32 s1, s0, 31
	s_lshl_b64 s[0:1], s[0:1], 11
	s_add_u32 s0, s19, s0
	v_lshl_add_u64 v[2:3], v[2:3], 0, s[42:43]
	s_addc_u32 s1, s21, s1
	global_load_lds_dwordx4 v[2:3], off
	v_lshl_add_u64 v[2:3], s[0:1], 0, v[0:1]
	v_readlane_b32 s1, v254, 9
	v_lshl_add_u64 v[4:5], v[2:3], 0, s[26:27]
	v_lshl_add_u64 v[2:3], v[2:3], 0, s[42:43]
	v_add_u32_e32 v155, s1, v142
	v_add_u32_e32 v156, 0x2000, v155
	v_readfirstlane_b32 s0, v155
	s_mov_b32 m0, s0
	v_readfirstlane_b32 s0, v156
	global_load_lds_dwordx4 v[4:5], off
	s_mov_b32 m0, s0
	v_and_b32_e32 v139, 15, v132
	global_load_lds_dwordx4 v[2:3], off
	v_lshlrev_b32_e32 v5, 2, v132
	v_and_b32_e32 v2, 48, v132
	v_lshlrev_b32_e32 v4, 6, v139
	v_and_b32_e32 v5, 32, v5
	v_bitop3_b32 v4, v4, v5, v2 bitop3:0x36
	v_readlane_b32 s0, v254, 7
	v_lshlrev_b32_e32 v11, 6, v132
	v_add_u32_e32 v9, s1, v4
	v_add_u32_e32 v7, s0, v4
	s_movk_i32 s0, 0x3c0
	v_and_or_b32 v2, v11, s0, v2
	s_add_i32 s0, s2, s3
	v_xad_u32 v5, v2, v5, 0
	v_lshlrev_b32_e32 v2, 14, v18
	s_ashr_i32 s1, s0, 31
	s_add_i32 s15, 0, 0x10000
	v_and_b32_e32 v2, 0xffff8000, v2
	s_lshl_b64 s[0:1], s[0:1], 11
	v_ashrrev_i32_e32 v140, 6, v138
	v_lshl_add_u32 v2, v19, 11, v2
	v_and_b32_e32 v14, 1, v18
	s_add_u32 s0, s10, s0
	v_and_b32_e32 v141, 3, v140
	s_waitcnt vmcnt(6)
	v_lshlrev_b32_e32 v10, 13, v21
	v_lshl_or_b32 v2, v14, 6, v2
	s_addc_u32 s1, s11, s1
	v_lshlrev_b32_e32 v3, 12, v141
	v_add_u32_e32 v6, s15, v4
	v_add_u32_e32 v8, s25, v4
	v_add_u32_e32 v4, 0, v4
	v_or_b32_e32 v11, 0x800, v10
	v_or_b32_e32 v12, 0x1000, v10
	v_or_b32_e32 v13, 0x1800, v10
	v_lshl_add_u32 v130, v20, 1, v2
	s_add_u32 s12, s22, s12
	v_mov_b32_e32 v2, 0
	v_lshlrev_b32_e32 v143, 6, v21
	v_mov_b32_e32 v131, v1
	s_addc_u32 s13, s23, s13
	s_mov_b32 s25, -2
	v_add_u32_e32 v157, v6, v3
	v_add_u32_e32 v147, v4, v10
	v_add_u32_e32 v146, v5, v11
	v_add_u32_e32 v145, v5, v12
	v_add_u32_e32 v144, v5, v13
	v_add_u32_e32 v154, v7, v3
	v_add_u32_e32 v149, v8, v3
	v_add_u32_e32 v148, v9, v3
	v_mov_b32_e32 v3, v2
	v_mov_b32_e32 v4, v2
	v_mov_b32_e32 v5, v2
	v_mov_b32_e32 v6, v2
	v_mov_b32_e32 v7, v2
	v_mov_b32_e32 v8, v2
	v_mov_b32_e32 v9, v2
	v_mov_b32_e32 v10, v2
	v_mov_b32_e32 v11, v2
	v_mov_b32_e32 v12, v2
	v_mov_b32_e32 v13, v2
	v_mov_b32_e32 v14, v2
	v_mov_b32_e32 v15, v2
	v_mov_b32_e32 v16, v2
	v_mov_b32_e32 v17, v2
	v_mov_b32_e32 v18, v2
	v_mov_b32_e32 v19, v2
	v_mov_b32_e32 v20, v2
	v_mov_b32_e32 v21, v2
	v_mov_b32_e32 v22, v2
	v_mov_b32_e32 v23, v2
	v_mov_b32_e32 v24, v2
	v_mov_b32_e32 v25, v2
	v_mov_b32_e32 v26, v2
	v_mov_b32_e32 v27, v2
	v_mov_b32_e32 v28, v2
	v_mov_b32_e32 v29, v2
	v_mov_b32_e32 v30, v2
	v_mov_b32_e32 v31, v2
	v_mov_b32_e32 v32, v2
	v_mov_b32_e32 v33, v2
	v_mov_b32_e32 v34, v2
	v_mov_b32_e32 v35, v2
	v_mov_b32_e32 v36, v2
	v_mov_b32_e32 v37, v2
	v_mov_b32_e32 v38, v2
	v_mov_b32_e32 v39, v2
	v_mov_b32_e32 v40, v2
	v_mov_b32_e32 v41, v2
	v_mov_b32_e32 v42, v2
	v_mov_b32_e32 v43, v2
	v_mov_b32_e32 v44, v2
	v_mov_b32_e32 v45, v2
	v_mov_b32_e32 v46, v2
	v_mov_b32_e32 v47, v2
	v_mov_b32_e32 v48, v2
	v_mov_b32_e32 v49, v2
	v_mov_b32_e32 v50, v2
	v_mov_b32_e32 v51, v2
	v_mov_b32_e32 v52, v2
	v_mov_b32_e32 v53, v2
	v_mov_b32_e32 v54, v2
	v_mov_b32_e32 v55, v2
	v_mov_b32_e32 v56, v2
	v_mov_b32_e32 v57, v2
	v_mov_b32_e32 v58, v2
	v_mov_b32_e32 v59, v2
	v_mov_b32_e32 v60, v2
	v_mov_b32_e32 v61, v2
	v_mov_b32_e32 v62, v2
	v_mov_b32_e32 v63, v2
	v_mov_b32_e32 v64, v2
	v_mov_b32_e32 v65, v2
	v_mov_b32_e32 v66, v2
	v_mov_b32_e32 v67, v2
	v_mov_b32_e32 v68, v2
	v_mov_b32_e32 v69, v2
	v_mov_b32_e32 v70, v2
	v_mov_b32_e32 v71, v2
	v_mov_b32_e32 v72, v2
	v_mov_b32_e32 v73, v2
	v_mov_b32_e32 v74, v2
	v_mov_b32_e32 v75, v2
	v_mov_b32_e32 v76, v2
	v_mov_b32_e32 v77, v2
	v_mov_b32_e32 v78, v2
	v_mov_b32_e32 v79, v2
	v_mov_b32_e32 v80, v2
	v_mov_b32_e32 v81, v2
	v_mov_b32_e32 v82, v2
	v_mov_b32_e32 v83, v2
	v_mov_b32_e32 v84, v2
	v_mov_b32_e32 v85, v2
	v_mov_b32_e32 v86, v2
	v_mov_b32_e32 v87, v2
	v_mov_b32_e32 v88, v2
	v_mov_b32_e32 v89, v2
	v_mov_b32_e32 v90, v2
	v_mov_b32_e32 v91, v2
	v_mov_b32_e32 v92, v2
	v_mov_b32_e32 v93, v2
	v_mov_b32_e32 v94, v2
	v_mov_b32_e32 v95, v2
	v_mov_b32_e32 v96, v2
	v_mov_b32_e32 v97, v2
	v_mov_b32_e32 v98, v2
	v_mov_b32_e32 v99, v2
	v_mov_b32_e32 v100, v2
	v_mov_b32_e32 v101, v2
	v_mov_b32_e32 v102, v2
	v_mov_b32_e32 v103, v2
	v_mov_b32_e32 v104, v2
	v_mov_b32_e32 v105, v2
	v_mov_b32_e32 v106, v2
	v_mov_b32_e32 v107, v2
	v_mov_b32_e32 v108, v2
	v_mov_b32_e32 v109, v2
	v_mov_b32_e32 v110, v2
	v_mov_b32_e32 v111, v2
	v_mov_b32_e32 v112, v2
	v_mov_b32_e32 v113, v2
	v_mov_b32_e32 v114, v2
	v_mov_b32_e32 v115, v2
	v_mov_b32_e32 v116, v2
	v_mov_b32_e32 v117, v2
	v_mov_b32_e32 v118, v2
	v_mov_b32_e32 v119, v2
	v_mov_b32_e32 v120, v2
	v_mov_b32_e32 v121, v2
	v_mov_b32_e32 v122, v2
	v_mov_b32_e32 v123, v2
	v_mov_b32_e32 v124, v2
	v_mov_b32_e32 v125, v2
	v_mov_b32_e32 v126, v2
	v_mov_b32_e32 v127, v2
	v_mov_b32_e32 v128, v2
	v_mov_b32_e32 v129, v2
	s_mov_b64 s[26:27], 0x8240080
	s_mov_b64 s[42:43], 0x8260080
	s_mov_b64 s[44:45], 0x8200100
	s_mov_b64 s[46:47], 0x8220100
	s_mov_b64 s[48:49], 0x8240100
	s_mov_b64 s[50:51], 0x8260100
	s_mov_b64 s[52:53], 0x8200180
	s_mov_b64 s[56:57], 0x8220180
	s_mov_b64 s[66:67], 0x20100
	s_mov_b64 s[76:77], 0x40100
	s_mov_b64 s[96:97], 0x60100
	s_mov_b64 vcc, 0x20180
	s_mov_b64 s[60:61], 0x40180
	s_mov_b64 s[94:95], 0x60180
	s_cmp_ge_u32 s33, 0x100
	s_cbranch_scc1 .Lprio_done_2
	s_setprio 1

; #define GPTR(T, ptr) ((__attribute__((address_space(1))) T*)(ptr))
; __device__ __forceinline__ float frsq(float x) { return __builtin_amdgcn_rsqf(x); }
; __device__ __forceinline__ int ptid_(int wave) { int l_; asm volatile("v_mbcnt_lo_u32_b32 %0, -1, 0\n\tv_mbcnt_hi_u32_b32 %0, -1, %0" : "=v"(l_)); return (wave << 6) | l_; }
; #define STAGE_B(P, br, kt) do { const char* _gb = (const char*)(Bt + ((long)(br) * K + (long)(kt) * BK)); \
;     __builtin_amdgcn_global_load_lds((const unsigned*)(_gb + bofl0), (unsigned*)((char*)(P) + gtid_ * 16), 16, 0, 0); \
;     __builtin_amdgcn_global_load_lds((const unsigned*)(_gb + (long)K * 128 + bofl0), (unsigned*)((char*)(P) + gtid_ * 16 + 8192), 16, 0, 0); } while (0)
; #define BAR __builtin_amdgcn_s_barrier()
; template <int EPI>
; __device__ __forceinline__ void gemm_tile(const GemmArgs& g, int brow, int bcol, int parity, bool first, bool nvalid, int nbrow, int nbcol) {
;     ...
;   int gtid_ = ptid_(g.tid);
;   const int wid = gtid_ >> 6, lane = gtid_ & 63, wr = wid >> 2, wc = wid & 3, fr = lane & 15, fq = lane >> 4;
;   unsigned aofl0, bofl0;
;   { int _r, _c; stage_rc(gtid_ * 16, _r, _c); aofl0 = (unsigned)(_r * lda + _c) * 2u; bofl0 = (unsigned)(_r * K + _c) * 2u; }
;   f32x4 acc[2][2][4][2] = {};
;   bf16x8 At[4][2], B0[2][2], B1[2][2];
;   const int nt = K / BK;
;   float* rstd_s = (float*)(smem + 153600) + (parity & 1) * 256;
;   if (first) {
;     WAIT_V(0);
;     __syncthreads();
;     STAGE_B(SB(0, 0), bcol, 0); STAGE_A(SA(0, 0), brow, 0);
;     STAGE_B(SB(0, 1), bcol + HALF, 0); STAGE_A(SA(0, 1), brow + HALF, 0);
;   }
;   f32x4 ra0, ra1, ra2, ra3;
;   if constexpr (EPI != EPI_RES) {
;     if (gtid_ < 256) {
;       const __attribute__((address_space(1))) f32x4* pp = GPTR(const f32x4, g.rowss + (long)(brow + gtid_) * 16);
;       ra0 = pp[0]; ra1 = pp[1]; ra2 = pp[2]; ra3 = pp[3];
;     }
;   }
;   if (wr == 1) BAR;
;   if (first) { WAIT_V(4); } else { WAIT_V(0); }
;   BAR;
;   if constexpr (EPI != EPI_RES) {
;     if (gtid_ < 256) {
;       float s = ((ra0[0] + ra0[1]) + (ra0[2] + ra0[3])) + ((ra1[0] + ra1[1]) + (ra1[2] + ra1[3])) + ((ra2[0] + ra2[1]) + (ra2[2] + ra2[3])) + ((ra3[0] + ra3[1]) + (ra3[2] + ra3[3]));
;       rstd_s[gtid_] = frsq(s * (1.0f / 1024.0f) + 1e-6f);
;     }
;   }
;   STAGE_B(SB(1, 0), bcol, 1); STAGE_A(SA(1, 0), brow, 1); STAGE_B(SB(1, 1), bcol + HALF, 1);
;   WAIT_V(6); BAR;
.LBB0_190:
	s_ashr_i32 s21, s20, 31
	s_lshl_b64 s[2:3], s[18:19], 1
	s_add_u32 s2, s48, s2
	v_readlane_b32 s18, v254, 8
	s_addc_u32 s3, s49, s3
	v_lshl_add_u64 v[6:7], s[2:3], 0, v[0:1]
	v_add_u32_e32 v152, s18, v146
	s_mov_b64 s[22:23], 0x80
	v_readfirstlane_b32 s12, v152
	s_add_u32 s2, s2, s50
	v_lshl_add_u64 v[6:7], v[6:7], 0, s[22:23]
	s_mov_b32 m0, s12
	s_addc_u32 s3, s3, 0
	v_add_u32_e32 v153, 0x2000, v152
	s_barrier
	global_load_lds_dwordx4 v[6:7], off
	v_lshl_add_u64 v[6:7], s[2:3], 0, v[0:1]
	v_readfirstlane_b32 s2, v153
	s_mov_b32 m0, s2
	s_lshl_b64 s[2:3], s[14:15], 1
	s_add_u32 s25, s47, s2
	s_addc_u32 s39, s46, s3
	s_add_u32 s2, s25, s96
	v_lshl_add_u64 v[6:7], v[6:7], 0, s[22:23]
	s_addc_u32 s3, s39, 0
	v_mov_b32_e32 v131, v1
	v_add_u32_e32 v155, 0x8000, v140
	global_load_lds_dwordx4 v[6:7], off
	v_lshl_add_u64 v[6:7], s[2:3], 0, v[130:131]
	v_readfirstlane_b32 s12, v155
	s_add_u32 s2, s2, s53
	v_lshl_add_u64 v[6:7], v[6:7], 0, s[22:23]
	s_mov_b32 m0, s12
	s_addc_u32 s3, s3, 0
	v_add_u32_e32 v156, 0xa000, v140
	global_load_lds_dwordx4 v[6:7], off
	v_lshl_add_u64 v[6:7], s[2:3], 0, v[130:131]
	v_readfirstlane_b32 s2, v156
	s_mov_b32 m0, s2
	s_or_b32 s2, s20, 0x80
	s_mul_hi_i32 s3, s2, s34
	s_mul_i32 s2, s2, s34
	s_lshl_b64 s[2:3], s[2:3], 1
	s_add_u32 s2, s48, s2
	v_readlane_b32 s14, v254, 9
	v_lshl_add_u64 v[6:7], v[6:7], 0, s[22:23]
	s_addc_u32 s3, s49, s3
	v_add_u32_e32 v157, s14, v146
	global_load_lds_dwordx4 v[6:7], off
	v_lshl_add_u64 v[6:7], s[2:3], 0, v[0:1]
	v_readfirstlane_b32 s12, v157
	s_add_u32 s2, s2, s50
	v_lshl_add_u64 v[6:7], v[6:7], 0, s[22:23]
	s_mov_b32 m0, s12
	s_addc_u32 s3, s3, 0
	v_add_u32_e32 v158, 0x2000, v157
	global_load_lds_dwordx4 v[6:7], off
	v_lshl_add_u64 v[6:7], s[2:3], 0, v[0:1]
	v_readfirstlane_b32 s2, v158
	v_lshl_add_u64 v[6:7], v[6:7], 0, s[22:23]
	s_mov_b32 m0, s2
	s_or_b32 s2, s38, 0x80
	global_load_lds_dwordx4 v[6:7], off
	v_and_b32_e32 v142, 15, v137
	v_lshlrev_b32_e32 v144, 2, v137
	s_mul_hi_i32 s3, s2, s37
	s_mul_i32 s2, s2, s37
	v_and_b32_e32 v7, 48, v137
	v_lshlrev_b32_e32 v8, 6, v142
	v_and_b32_e32 v9, 32, v144
	s_add_i32 s40, 0, 0x10000
	s_lshl_b64 s[12:13], s[2:3], 1
	v_bitop3_b32 v8, v8, v9, v7 bitop3:0x36
	s_add_u32 s41, s47, s12
	v_readlane_b32 s2, v254, 7
	s_addc_u32 s44, s46, s13
	v_lshlrev_b32_e32 v14, 6, v137
	v_add_u32_e32 v11, s2, v8
	s_movk_i32 s2, 0x3c0
	s_mul_i32 s3, s74, s20
	v_add_u32_e32 v13, s14, v8
	v_and_or_b32 v7, v14, s2, v7
	s_mul_hi_i32 s2, s74, s20
	s_add_u32 s14, s31, s3
	s_addc_u32 s15, s73, s2
	s_lshl_b64 s[2:3], s[20:21], 1
	v_add_u32_e32 v12, s18, v8
	s_add_u32 s18, s2, 0x80
	s_addc_u32 s19, s3, 0
	s_mul_i32 s19, s34, s19
	s_mul_hi_u32 s22, s34, s18
	s_add_i32 s22, s22, s19
	s_mul_i32 s18, s34, s18
	s_add_u32 s18, s31, s18
	s_addc_u32 s19, s73, s22
	s_add_u32 s20, s20, 0x80
	s_addc_u32 s21, s21, 0
	s_mul_i32 s21, s74, s21
	s_mul_hi_u32 s22, s74, s20
	s_add_i32 s22, s22, s21
	s_mul_i32 s20, s74, s20
	s_add_u32 s20, s31, s20
	s_addc_u32 s21, s73, s22
	s_add_u32 s2, s2, 0x180
	s_addc_u32 s3, s3, 0
	v_ashrrev_i32_e32 v143, 6, v141
	s_mul_i32 s3, s34, s3
	s_mul_hi_u32 s22, s34, s2
	v_and_b32_e32 v138, 3, v143
	s_waitcnt vmcnt(6)
	v_lshlrev_b32_e32 v145, 6, v5
	v_lshlrev_b32_e32 v5, 13, v5
	v_add_u32_e32 v2, v4, v2
	s_add_i32 s3, s22, s3
	s_mul_i32 s2, s34, s2
	v_lshlrev_b32_e32 v6, 12, v138
	v_add_u32_e32 v10, s40, v8
	v_add_u32_e32 v8, 0, v8
	v_xad_u32 v7, v7, v9, 0
	v_or_b32_e32 v9, 0x800, v5
	v_or_b32_e32 v14, 0x1000, v5
	v_or_b32_e32 v15, 0x1800, v5
	v_add_lshl_u32 v132, v2, v3, 1
	s_add_u32 s22, s31, s2
	v_mov_b32_e32 v2, 0
	v_mov_b32_e32 v133, v1
	s_addc_u32 s23, s73, s3
	s_mov_b32 s45, 0
	s_movk_i32 s61, 0xc0
	v_add_u32_e32 v160, v10, v6
	v_add_u32_e32 v150, v8, v5
	v_add_u32_e32 v149, v7, v9
	v_add_u32_e32 v148, v7, v14
	v_add_u32_e32 v147, v7, v15
	v_add_u32_e32 v159, v11, v6
	v_add_u32_e32 v154, v12, v6
	v_add_u32_e32 v151, v13, v6
	v_mov_b32_e32 v3, v2
	v_mov_b32_e32 v4, v2
	v_mov_b32_e32 v5, v2
	v_mov_b32_e32 v6, v2
	v_mov_b32_e32 v7, v2
	v_mov_b32_e32 v8, v2
	v_mov_b32_e32 v9, v2
	v_mov_b32_e32 v10, v2
	v_mov_b32_e32 v11, v2
	v_mov_b32_e32 v12, v2
	v_mov_b32_e32 v13, v2
	v_mov_b32_e32 v14, v2
	v_mov_b32_e32 v15, v2
	v_mov_b32_e32 v16, v2
	v_mov_b32_e32 v17, v2
	v_mov_b32_e32 v18, v2
	v_mov_b32_e32 v19, v2
	v_mov_b32_e32 v20, v2
	v_mov_b32_e32 v21, v2
	v_mov_b32_e32 v22, v2
	v_mov_b32_e32 v23, v2
	v_mov_b32_e32 v24, v2
	v_mov_b32_e32 v25, v2
	v_mov_b32_e32 v26, v2
	v_mov_b32_e32 v27, v2
	v_mov_b32_e32 v28, v2
	v_mov_b32_e32 v29, v2
	v_mov_b32_e32 v30, v2
	v_mov_b32_e32 v31, v2
	v_mov_b32_e32 v32, v2
	v_mov_b32_e32 v33, v2
	v_mov_b32_e32 v34, v2
	v_mov_b32_e32 v35, v2
	v_mov_b32_e32 v36, v2
	v_mov_b32_e32 v37, v2
	v_mov_b32_e32 v38, v2
	v_mov_b32_e32 v39, v2
	v_mov_b32_e32 v40, v2
	v_mov_b32_e32 v41, v2
	v_mov_b32_e32 v42, v2
	v_mov_b32_e32 v43, v2
	v_mov_b32_e32 v44, v2
	v_mov_b32_e32 v45, v2
	v_mov_b32_e32 v46, v2
	v_mov_b32_e32 v47, v2
	v_mov_b32_e32 v48, v2
	v_mov_b32_e32 v49, v2
	v_mov_b32_e32 v50, v2
	v_mov_b32_e32 v51, v2
	v_mov_b32_e32 v52, v2
	v_mov_b32_e32 v53, v2
	v_mov_b32_e32 v54, v2
	v_mov_b32_e32 v55, v2
	v_mov_b32_e32 v56, v2
	v_mov_b32_e32 v57, v2
	v_mov_b32_e32 v58, v2
	v_mov_b32_e32 v59, v2
	v_mov_b32_e32 v60, v2
	v_mov_b32_e32 v61, v2
	v_mov_b32_e32 v62, v2
	v_mov_b32_e32 v63, v2
	v_mov_b32_e32 v64, v2
	v_mov_b32_e32 v65, v2
	v_mov_b32_e32 v66, v2
	v_mov_b32_e32 v67, v2
	v_mov_b32_e32 v68, v2
	v_mov_b32_e32 v69, v2
	v_mov_b32_e32 v70, v2
	v_mov_b32_e32 v71, v2
	v_mov_b32_e32 v72, v2
	v_mov_b32_e32 v73, v2
	v_mov_b32_e32 v74, v2
	v_mov_b32_e32 v75, v2
	v_mov_b32_e32 v76, v2
	v_mov_b32_e32 v77, v2
	v_mov_b32_e32 v78, v2
	v_mov_b32_e32 v79, v2
	v_mov_b32_e32 v80, v2
	v_mov_b32_e32 v81, v2
	v_mov_b32_e32 v82, v2
	v_mov_b32_e32 v83, v2
	v_mov_b32_e32 v84, v2
	v_mov_b32_e32 v85, v2
	v_mov_b32_e32 v86, v2
	v_mov_b32_e32 v87, v2
	v_mov_b32_e32 v88, v2
	v_mov_b32_e32 v89, v2
	v_mov_b32_e32 v90, v2
	v_mov_b32_e32 v91, v2
	v_mov_b32_e32 v92, v2
	v_mov_b32_e32 v93, v2
	v_mov_b32_e32 v94, v2
	v_mov_b32_e32 v95, v2
	v_mov_b32_e32 v96, v2
	v_mov_b32_e32 v97, v2
	v_mov_b32_e32 v98, v2
	v_mov_b32_e32 v99, v2
	v_mov_b32_e32 v100, v2
	v_mov_b32_e32 v101, v2
	v_mov_b32_e32 v102, v2
	v_mov_b32_e32 v103, v2
	v_mov_b32_e32 v104, v2
	v_mov_b32_e32 v105, v2
	v_mov_b32_e32 v106, v2
	v_mov_b32_e32 v107, v2
	v_mov_b32_e32 v108, v2
	v_mov_b32_e32 v109, v2
	v_mov_b32_e32 v110, v2
	v_mov_b32_e32 v111, v2
	v_mov_b32_e32 v112, v2
	v_mov_b32_e32 v113, v2
	v_mov_b32_e32 v114, v2
	v_mov_b32_e32 v115, v2
	v_mov_b32_e32 v116, v2
	v_mov_b32_e32 v117, v2
	v_mov_b32_e32 v118, v2
	v_mov_b32_e32 v119, v2
	v_mov_b32_e32 v120, v2
	v_mov_b32_e32 v121, v2
	v_mov_b32_e32 v122, v2
	v_mov_b32_e32 v123, v2
	v_mov_b32_e32 v124, v2
	v_mov_b32_e32 v125, v2
	v_mov_b32_e32 v126, v2
	v_mov_b32_e32 v127, v2
	v_mov_b32_e32 v128, v2
	v_mov_b32_e32 v129, v2
	s_cmp_ge_u32 s33, 0x100
	s_cbranch_scc1 .Lprio_done_3
	s_setprio 1

; #define GPTR(T, ptr) ((__attribute__((address_space(1))) T*)(ptr))
; __device__ __forceinline__ float frsq(float x) { return __builtin_amdgcn_rsqf(x); }
; __device__ __forceinline__ int ptid_(int wave) { int l_; asm volatile("v_mbcnt_lo_u32_b32 %0, -1, 0\n\tv_mbcnt_hi_u32_b32 %0, -1, %0" : "=v"(l_)); return (wave << 6) | l_; }
; #define STAGE_B(P, br, kt) do { const char* _gb = (const char*)(Bt + ((long)(br) * K + (long)(kt) * BK)); \
;     __builtin_amdgcn_global_load_lds((const unsigned*)(_gb + bofl0), (unsigned*)((char*)(P) + gtid_ * 16), 16, 0, 0); \
;     __builtin_amdgcn_global_load_lds((const unsigned*)(_gb + (long)K * 128 + bofl0), (unsigned*)((char*)(P) + gtid_ * 16 + 8192), 16, 0, 0); } while (0)
; #define BAR __builtin_amdgcn_s_barrier()
; template <int EPI>
; __device__ __forceinline__ void gemm_tile(const GemmArgs& g, int brow, int bcol, int parity, bool first, bool nvalid, int nbrow, int nbcol) {
;     ...
;   int gtid_ = ptid_(g.tid);
;   const int wid = gtid_ >> 6, lane = gtid_ & 63, wr = wid >> 2, wc = wid & 3, fr = lane & 15, fq = lane >> 4;
;   unsigned aofl0, bofl0;
;   { int _r, _c; stage_rc(gtid_ * 16, _r, _c); aofl0 = (unsigned)(_r * lda + _c) * 2u; bofl0 = (unsigned)(_r * K + _c) * 2u; }
;   f32x4 acc[2][2][4][2] = {};
;   bf16x8 At[4][2], B0[2][2], B1[2][2];
;   const int nt = K / BK;
;   float* rstd_s = (float*)(smem + 153600) + (parity & 1) * 256;
;   if (first) {
;     WAIT_V(0);
;     __syncthreads();
;     STAGE_B(SB(0, 0), bcol, 0); STAGE_A(SA(0, 0), brow, 0);
;     STAGE_B(SB(0, 1), bcol + HALF, 0); STAGE_A(SA(0, 1), brow + HALF, 0);
;   }
;   f32x4 ra0, ra1, ra2, ra3;
;   if constexpr (EPI != EPI_RES) {
;     if (gtid_ < 256) {
;       const __attribute__((address_space(1))) f32x4* pp = GPTR(const f32x4, g.rowss + (long)(brow + gtid_) * 16);
;       ra0 = pp[0]; ra1 = pp[1]; ra2 = pp[2]; ra3 = pp[3];
;     }
;   }
;   if (wr == 1) BAR;
;   if (first) { WAIT_V(4); } else { WAIT_V(0); }
;   BAR;
;   if constexpr (EPI != EPI_RES) {
;     if (gtid_ < 256) {
;       float s = ((ra0[0] + ra0[1]) + (ra0[2] + ra0[3])) + ((ra1[0] + ra1[1]) + (ra1[2] + ra1[3])) + ((ra2[0] + ra2[1]) + (ra2[2] + ra2[3])) + ((ra3[0] + ra3[1]) + (ra3[2] + ra3[3]));
;       rstd_s[gtid_] = frsq(s * (1.0f / 1024.0f) + 1e-6f);
;     }
;   }
;   STAGE_B(SB(1, 0), bcol, 1); STAGE_A(SA(1, 0), brow, 1); STAGE_B(SB(1, 1), bcol + HALF, 1);
;   WAIT_V(6); BAR;
.LBB0_639:
	s_or_b64 exec, exec, s[0:1]
	s_ashr_i32 s13, s12, 31
	s_lshl_b64 s[0:1], s[12:13], 11
	s_add_u32 s0, s70, s0
	v_readlane_b32 s15, v255, 0
	v_readlane_b32 s23, v254, 8
	s_addc_u32 s1, s15, s1
	s_ashr_i32 s41, s40, 31
	v_add_u32_e32 v150, s23, v142
	s_waitcnt vmcnt(0)
	v_lshl_add_u64 v[2:3], s[0:1], 0, v[0:1]
	s_mov_b64 s[36:37], 0x80
	v_readfirstlane_b32 s13, v150
	v_add_u32_e32 v151, 0x2000, v150
	s_lshl_b64 s[24:25], s[40:41], 11
	v_lshl_add_u64 v[4:5], v[2:3], 0, s[36:37]
	s_mov_b32 m0, s13
	s_mov_b64 s[38:39], 0x20080
	v_readfirstlane_b32 s13, v151
	s_add_u32 s24, s80, s24
	global_load_lds_dwordx4 v[4:5], off
	v_lshl_add_u64 v[2:3], v[2:3], 0, s[38:39]
	s_mov_b32 m0, s13
	s_addc_u32 s25, s81, s25
	v_add_u32_e32 v152, 0x8000, v137
	global_load_lds_dwordx4 v[2:3], off
	v_lshl_add_u64 v[2:3], s[24:25], 0, v[0:1]
	v_readfirstlane_b32 s13, v152
	v_add_u32_e32 v153, 0xa000, v137
	v_lshl_add_u64 v[4:5], v[2:3], 0, s[36:37]
	s_mov_b32 m0, s13
	v_readfirstlane_b32 s13, v153
	s_bitset1_b32 s12, 7
	global_load_lds_dwordx4 v[4:5], off
	s_mov_b32 m0, s13
	s_ashr_i32 s13, s12, 31
	s_lshl_b64 s[12:13], s[12:13], 11
	s_add_u32 s12, s70, s12
	v_lshl_add_u64 v[2:3], v[2:3], 0, s[38:39]
	s_addc_u32 s13, s15, s13
	global_load_lds_dwordx4 v[2:3], off
	v_lshl_add_u64 v[2:3], s[12:13], 0, v[0:1]
	v_readlane_b32 s13, v254, 9
	v_lshl_add_u64 v[4:5], v[2:3], 0, s[36:37]
	v_lshl_add_u64 v[2:3], v[2:3], 0, s[38:39]
	v_add_u32_e32 v155, s13, v142
	v_add_u32_e32 v156, 0x2000, v155
	v_readfirstlane_b32 s12, v155
	s_mov_b32 m0, s12
	v_readfirstlane_b32 s12, v156
	global_load_lds_dwordx4 v[4:5], off
	s_mov_b32 m0, s12
	v_and_b32_e32 v139, 15, v132
	global_load_lds_dwordx4 v[2:3], off
	v_lshlrev_b32_e32 v5, 2, v132
	v_and_b32_e32 v2, 48, v132
	v_lshlrev_b32_e32 v4, 6, v139
	v_and_b32_e32 v5, 32, v5
	v_bitop3_b32 v4, v4, v5, v2 bitop3:0x36
	v_readlane_b32 s12, v254, 7
	v_lshlrev_b32_e32 v11, 6, v132
	s_add_i32 s2, s2, s3
	v_add_u32_e32 v7, s12, v4
	s_movk_i32 s12, 0x3c0
	v_and_or_b32 v2, v11, s12, v2
	v_xad_u32 v5, v2, v5, 0
	v_lshlrev_b32_e32 v2, 14, v18
	v_and_b32_e32 v2, 0xffff8000, v2
	v_ashrrev_i32_e32 v140, 6, v138
	v_lshl_add_u32 v2, v19, 11, v2
	v_and_b32_e32 v14, 1, v18
	s_ashr_i32 s3, s2, 31
	v_and_b32_e32 v141, 3, v140
	s_waitcnt vmcnt(6)
	s_add_i32 s15, 0, 0x10000
	v_lshlrev_b32_e32 v10, 13, v21
	v_lshl_or_b32 v2, v14, 6, v2
	s_lshl_b64 s[2:3], s[2:3], 11
	v_lshlrev_b32_e32 v3, 12, v141
	v_add_u32_e32 v6, s15, v4
	v_add_u32_e32 v8, s23, v4
	v_add_u32_e32 v9, s13, v4
	v_add_u32_e32 v4, 0, v4
	v_or_b32_e32 v11, 0x800, v10
	v_or_b32_e32 v12, 0x1000, v10
	v_or_b32_e32 v13, 0x1800, v10
	v_lshl_add_u32 v130, v20, 1, v2
	s_add_u32 s12, s10, s2
	v_mov_b32_e32 v2, 0
	v_lshlrev_b32_e32 v143, 6, v21
	v_mov_b32_e32 v131, v1
	s_addc_u32 s13, s11, s3
	s_mov_b32 s23, -2
	v_add_u32_e32 v157, v6, v3
	v_add_u32_e32 v147, v4, v10
	v_add_u32_e32 v146, v5, v11
	v_add_u32_e32 v145, v5, v12
	v_add_u32_e32 v144, v5, v13
	v_add_u32_e32 v154, v7, v3
	v_add_u32_e32 v149, v8, v3
	v_add_u32_e32 v148, v9, v3
	v_mov_b32_e32 v3, v2
	v_mov_b32_e32 v4, v2
	v_mov_b32_e32 v5, v2
	v_mov_b32_e32 v6, v2
	v_mov_b32_e32 v7, v2
	v_mov_b32_e32 v8, v2
	v_mov_b32_e32 v9, v2
	v_mov_b32_e32 v10, v2
	v_mov_b32_e32 v11, v2
	v_mov_b32_e32 v12, v2
	v_mov_b32_e32 v13, v2
	v_mov_b32_e32 v14, v2
	v_mov_b32_e32 v15, v2
	v_mov_b32_e32 v16, v2
	v_mov_b32_e32 v17, v2
	v_mov_b32_e32 v18, v2
	v_mov_b32_e32 v19, v2
	v_mov_b32_e32 v20, v2
	v_mov_b32_e32 v21, v2
	v_mov_b32_e32 v22, v2
	v_mov_b32_e32 v23, v2
	v_mov_b32_e32 v24, v2
	v_mov_b32_e32 v25, v2
	v_mov_b32_e32 v26, v2
	v_mov_b32_e32 v27, v2
	v_mov_b32_e32 v28, v2
	v_mov_b32_e32 v29, v2
	v_mov_b32_e32 v30, v2
	v_mov_b32_e32 v31, v2
	v_mov_b32_e32 v32, v2
	v_mov_b32_e32 v33, v2
	v_mov_b32_e32 v34, v2
	v_mov_b32_e32 v35, v2
	v_mov_b32_e32 v36, v2
	v_mov_b32_e32 v37, v2
	v_mov_b32_e32 v38, v2
	v_mov_b32_e32 v39, v2
	v_mov_b32_e32 v40, v2
	v_mov_b32_e32 v41, v2
	v_mov_b32_e32 v42, v2
	v_mov_b32_e32 v43, v2
	v_mov_b32_e32 v44, v2
	v_mov_b32_e32 v45, v2
	v_mov_b32_e32 v46, v2
	v_mov_b32_e32 v47, v2
	v_mov_b32_e32 v48, v2
	v_mov_b32_e32 v49, v2
	v_mov_b32_e32 v50, v2
	v_mov_b32_e32 v51, v2
	v_mov_b32_e32 v52, v2
	v_mov_b32_e32 v53, v2
	v_mov_b32_e32 v54, v2
	v_mov_b32_e32 v55, v2
	v_mov_b32_e32 v56, v2
	v_mov_b32_e32 v57, v2
	v_mov_b32_e32 v58, v2
	v_mov_b32_e32 v59, v2
	v_mov_b32_e32 v60, v2
	v_mov_b32_e32 v61, v2
	v_mov_b32_e32 v62, v2
	v_mov_b32_e32 v63, v2
	v_mov_b32_e32 v64, v2
	v_mov_b32_e32 v65, v2
	v_mov_b32_e32 v66, v2
	v_mov_b32_e32 v67, v2
	v_mov_b32_e32 v68, v2
	v_mov_b32_e32 v69, v2
	v_mov_b32_e32 v70, v2
	v_mov_b32_e32 v71, v2
	v_mov_b32_e32 v72, v2
	v_mov_b32_e32 v73, v2
	v_mov_b32_e32 v74, v2
	v_mov_b32_e32 v75, v2
	v_mov_b32_e32 v76, v2
	v_mov_b32_e32 v77, v2
	v_mov_b32_e32 v78, v2
	v_mov_b32_e32 v79, v2
	v_mov_b32_e32 v80, v2
	v_mov_b32_e32 v81, v2
	v_mov_b32_e32 v82, v2
	v_mov_b32_e32 v83, v2
	v_mov_b32_e32 v84, v2
	v_mov_b32_e32 v85, v2
	v_mov_b32_e32 v86, v2
	v_mov_b32_e32 v87, v2
	v_mov_b32_e32 v88, v2
	v_mov_b32_e32 v89, v2
	v_mov_b32_e32 v90, v2
	v_mov_b32_e32 v91, v2
	v_mov_b32_e32 v92, v2
	v_mov_b32_e32 v93, v2
	v_mov_b32_e32 v94, v2
	v_mov_b32_e32 v95, v2
	v_mov_b32_e32 v96, v2
	v_mov_b32_e32 v97, v2
	v_mov_b32_e32 v98, v2
	v_mov_b32_e32 v99, v2
	v_mov_b32_e32 v100, v2
	v_mov_b32_e32 v101, v2
	v_mov_b32_e32 v102, v2
	v_mov_b32_e32 v103, v2
	v_mov_b32_e32 v104, v2
	v_mov_b32_e32 v105, v2
	v_mov_b32_e32 v106, v2
	v_mov_b32_e32 v107, v2
	v_mov_b32_e32 v108, v2
	v_mov_b32_e32 v109, v2
	v_mov_b32_e32 v110, v2
	v_mov_b32_e32 v111, v2
	v_mov_b32_e32 v112, v2
	v_mov_b32_e32 v113, v2
	v_mov_b32_e32 v114, v2
	v_mov_b32_e32 v115, v2
	v_mov_b32_e32 v116, v2
	v_mov_b32_e32 v117, v2
	v_mov_b32_e32 v118, v2
	v_mov_b32_e32 v119, v2
	v_mov_b32_e32 v120, v2
	v_mov_b32_e32 v121, v2
	v_mov_b32_e32 v122, v2
	v_mov_b32_e32 v123, v2
	v_mov_b32_e32 v124, v2
	v_mov_b32_e32 v125, v2
	v_mov_b32_e32 v126, v2
	v_mov_b32_e32 v127, v2
	v_mov_b32_e32 v128, v2
	v_mov_b32_e32 v129, v2
	s_mov_b64 s[24:25], 0x8240080
	s_mov_b64 s[36:37], 0x8260080
	s_mov_b64 s[38:39], 0x8200100
	s_mov_b64 s[42:43], 0x8220100
	s_mov_b64 s[44:45], 0x8240100
	s_mov_b64 s[46:47], 0x8260100
	s_mov_b64 s[48:49], 0x8200180
	s_mov_b64 s[50:51], 0x8220180
	s_mov_b64 s[66:67], 0x20100
	s_mov_b64 s[76:77], 0x40100
	s_mov_b64 s[96:97], 0x60100
	s_mov_b64 vcc, 0x20180
	s_mov_b64 s[60:61], 0x40180
	s_mov_b64 s[94:95], 0x60180
	s_cmp_ge_u32 s33, 0x100
	s_cbranch_scc1 .Lprio_done_4
	s_setprio 1
